# stacked on v53: attention unit prologue q-norm trim (4 LDS reads together, DPP wave max) and LN_in x pointer kept in SGPRs
# speedup vs baseline: 1.0190x; 1.0052x over previous
.LBB0_79:
	s_mov_b64 s[4:5], s[0:1]
	s_load_dwordx2 s[4:5], s[4:5], 0x8
	v_lshlrev_b64 v[66:67], 4, v[68:69]
	s_mov_b64 s[6:7], s[0:1]
	s_waitcnt vmcnt(3)
	v_and_b32_e32 v30, 0xffffffc0, v220
	v_add_u32_e32 v30, 64, v30
	s_waitcnt lgkmcnt(0)
	v_lshl_add_u64 v[2:3], s[4:5], 0, v[66:67]
	global_load_dwordx4 v[2:5], v[2:3], off
	s_load_dwordx2 s[4:5], s[6:7], 0x10
	s_mov_b64 s[6:7], s[0:1]
	s_waitcnt vmcnt(3)
	v_xor_b32_e32 v31, 1, v220
	v_cmp_lt_i32_e32 vcc, v31, v30
	s_movk_i32 s12, 0x7fff
	s_waitcnt lgkmcnt(0)
	v_lshl_add_u64 v[6:7], s[4:5], 0, v[66:67]
	global_load_dwordx4 v[6:9], v[6:7], off
	s_load_dwordx2 s[4:5], s[6:7], 0x8
	s_mov_b64 s[6:7], s[0:1]
	v_cndmask_b32_e32 v31, v220, v31, vcc
	v_lshlrev_b32_e32 v221, 2, v31
	v_xor_b32_e32 v31, 2, v220
	s_waitcnt lgkmcnt(0)
	v_lshl_add_u64 v[10:11], s[4:5], 0, v[66:67]
	global_load_dwordx4 v[10:13], v[10:11], off offset:1024
	s_load_dwordx2 s[4:5], s[6:7], 0x10
	s_mov_b64 s[6:7], s[0:1]
	v_cmp_lt_i32_e32 vcc, v31, v30
	s_cmpk_gt_u32 s86, 0x7fff
	s_waitcnt lgkmcnt(0)
	v_lshl_add_u64 v[14:15], s[4:5], 0, v[66:67]
	global_load_dwordx4 v[14:17], v[14:15], off offset:1024
	s_load_dwordx2 s[4:5], s[6:7], 0x8
	s_mov_b64 s[6:7], s[0:1]
	v_cndmask_b32_e32 v31, v220, v31, vcc
	v_lshlrev_b32_e32 v222, 2, v31
	v_xor_b32_e32 v31, 4, v220
	s_waitcnt lgkmcnt(0)
	v_lshl_add_u64 v[18:19], s[4:5], 0, v[66:67]
	global_load_dwordx4 v[18:21], v[18:19], off offset:2048
	s_load_dwordx2 s[4:5], s[6:7], 0x10
	s_mov_b64 s[6:7], s[0:1]
	v_cmp_lt_i32_e32 vcc, v31, v30
	s_waitcnt lgkmcnt(0)
	v_lshl_add_u64 v[22:23], s[4:5], 0, v[66:67]
	global_load_dwordx4 v[22:25], v[22:23], off offset:2048
	s_load_dwordx2 s[4:5], s[6:7], 0x8
	v_cndmask_b32_e32 v31, v220, v31, vcc
	v_lshlrev_b32_e32 v223, 2, v31
	v_xor_b32_e32 v31, 8, v220
	v_cmp_lt_i32_e32 vcc, v31, v30
	s_waitcnt lgkmcnt(0)
	v_lshl_add_u64 v[26:27], s[4:5], 0, v[66:67]
	global_load_dwordx4 v[26:29], v[26:27], off offset:3072
	v_cndmask_b32_e32 v31, v220, v31, vcc
	v_lshlrev_b32_e32 v224, 2, v31
	v_xor_b32_e32 v31, 16, v220
	v_cmp_lt_i32_e32 vcc, v31, v30
	s_mov_b64 s[4:5], s[0:1]
	s_nop 0
	v_cndmask_b32_e32 v31, v220, v31, vcc
	v_lshlrev_b32_e32 v225, 2, v31
	v_xor_b32_e32 v31, 32, v220
	v_cmp_lt_i32_e32 vcc, v31, v30
	s_nop 1
	v_cndmask_b32_e32 v30, v220, v31, vcc
	v_lshlrev_b32_e32 v226, 2, v30
	s_cbranch_scc1 .LBB0_82
	s_load_dwordx2 s[98:99], s[0:1], 0x0
	s_load_dwordx2 s[4:5], s[4:5], 0x10
	s_mov_b32 s17, 0
	v_mov_b32_e32 v72, 0x3727c5ac
	s_mov_b32 s33, 0xf800000
	v_mov_b32_e32 v73, 0x260
	s_waitcnt lgkmcnt(0)
	v_lshl_add_u64 v[30:31], v[68:69], 4, s[4:5]
	global_load_dwordx4 v[30:33], v[30:31], off offset:3072
	s_and_b32 s4, s2, 7
	s_lshl_b32 s4, s4, 8
	v_readlane_b32 s5, v245, 2
	s_add_i32 s4, s5, s4
	s_lshl_b32 s5, s82, 3
	s_add_i32 s4, s4, s5
	s_add_i32 s13, s4, 0xfffff000
	s_lshl_b32 s4, s4, 10
	s_add_i32 s14, s4, 0x200000
	s_mov_b32 s38, 0xffff0000
	s_mov_b32 s39, 0x7200000
	v_lshlrev_b64 v[68:69], 3, v[68:69]
.LBB0_81:
	s_mov_b64 s[4:5], s[98:99]
	s_add_i32 s16, s14, 0xffe00000
	s_mov_b64 s[6:7], s[98:99]
	s_lshl_b64 s[34:35], s[16:17], 2
	s_add_u32 s4, s4, s34
	s_mov_b32 s15, s17
	s_addc_u32 s5, s5, s35
	s_lshl_b64 s[34:35], s[14:15], 2
	v_lshl_add_u64 v[34:35], s[4:5], 0, v[66:67]
	s_add_u32 s4, s6, s34
	global_load_dwordx4 v[62:65], v[34:35], off
	global_load_dwordx4 v[58:61], v[34:35], off offset:1024
	global_load_dwordx4 v[50:53], v[34:35], off offset:2048
	global_load_dwordx4 v[54:57], v[34:35], off offset:3072
	s_addc_u32 s5, s7, s35
	v_lshl_add_u64 v[70:71], s[4:5], 0, v[66:67]
	global_load_dwordx4 v[46:49], v[70:71], off
	global_load_dwordx4 v[42:45], v[70:71], off offset:1024
	global_load_dwordx4 v[38:41], v[70:71], off offset:2048
	global_load_dwordx4 v[34:37], v[70:71], off offset:3072
	s_mov_b64 s[36:37], s[0:1]
	s_load_dwordx2 s[4:5], s[36:37], 0x80
	s_lshl_b64 s[34:35], s[16:17], 1
	s_mov_b64 s[18:19], s[0:1]
	s_mov_b64 s[20:21], s[0:1]
	s_mov_b64 s[22:23], s[0:1]
	s_waitcnt lgkmcnt(0)
	s_add_u32 s4, s4, s34
	s_addc_u32 s5, s5, s35
	v_lshl_add_u64 v[70:71], s[4:5], 0, v[68:69]
	v_add_co_u32_e32 v70, vcc, s39, v70
	s_lshl_b64 s[36:37], s[14:15], 1
	s_nop 0
	v_addc_co_u32_e32 v71, vcc, 0, v71, vcc
	s_mov_b64 s[24:25], s[0:1]
	s_mov_b64 s[26:27], s[0:1]
	s_mov_b64 s[28:29], s[0:1]
	s_mov_b64 s[30:31], s[0:1]
	s_waitcnt vmcnt(7)
	v_mov_b32_e32 v74, v63
	v_mov_b32_e32 v75, v64
	v_mov_b32_e32 v76, v62
	v_mov_b32_e32 v77, v65
	s_waitcnt vmcnt(6)
	v_mov_b32_e32 v78, v59
	v_mov_b32_e32 v79, v60
	v_mov_b32_e32 v80, v58
	v_mov_b32_e32 v81, v61
	s_waitcnt vmcnt(5)
	v_add_f32_e32 v82, v50, v51
	v_add_f32_e32 v84, v52, v53
	s_waitcnt vmcnt(4)
	v_mov_b32_e32 v83, v56
	v_mov_b32_e32 v85, v57
	v_pk_add_f32 v[74:75], v[74:75], v[76:77]
	v_pk_add_f32 v[76:77], v[78:79], v[80:81]
	v_pk_add_f32 v[78:79], v[82:83], v[84:85]
	v_add_f32_e32 v86, v74, v75
	s_waitcnt vmcnt(3)
	v_mov_b32_e32 v74, v47
	v_mov_b32_e32 v75, v48
	v_mov_b32_e32 v80, v46
	v_mov_b32_e32 v81, v49
	v_pk_add_f32 v[76:77], v[76:77], v[76:77] op_sel:[0,1] op_sel_hi:[1,0]
	s_waitcnt vmcnt(2)
	v_mov_b32_e32 v82, v43
	v_mov_b32_e32 v83, v44
	v_mov_b32_e32 v84, v42
	v_mov_b32_e32 v85, v45
	v_mov_b32_e32 v87, v54
	v_add_f32_e32 v86, 0, v86
	v_pk_add_f32 v[74:75], v[74:75], v[80:81]
	v_pk_add_f32 v[80:81], v[82:83], v[84:85]
	v_mov_b32_e32 v77, v55
	v_add_f32_e32 v84, v74, v75
	v_pk_add_f32 v[74:75], v[80:81], v[80:81] op_sel:[0,1] op_sel_hi:[1,0]
	v_pk_add_f32 v[76:77], v[86:87], v[76:77]
	s_waitcnt vmcnt(1)
	v_add_f32_e32 v88, v38, v39
	v_add_f32_e32 v90, v40, v41
	s_waitcnt vmcnt(0)
	v_mov_b32_e32 v93, v34
	v_mov_b32_e32 v89, v36
	v_mov_b32_e32 v91, v37
	v_add_f32_e32 v92, 0, v84
	v_pk_add_f32 v[76:77], v[76:77], v[78:79]
	v_mov_b32_e32 v75, v35
	v_pk_add_f32 v[82:83], v[88:89], v[90:91]
	v_add_f32_e32 v76, v76, v77
	v_pk_add_f32 v[74:75], v[92:93], v[74:75]
	v_pk_add_f32 v[74:75], v[74:75], v[82:83]
	s_nop 0
	v_add_f32_e32 v74, v74, v75
	s_nop 1
	v_add_f32_dpp v76, v76, v76 quad_perm:[1,0,3,2] row_mask:0xf bank_mask:0xf
	v_add_f32_dpp v74, v74, v74 quad_perm:[1,0,3,2] row_mask:0xf bank_mask:0xf
	s_nop 1
	v_add_f32_dpp v76, v76, v76 quad_perm:[2,3,0,1] row_mask:0xf bank_mask:0xf
	v_add_f32_dpp v74, v74, v74 quad_perm:[2,3,0,1] row_mask:0xf bank_mask:0xf
	s_nop 1
	v_add_f32_dpp v76, v76, v76 row_ror:4 row_mask:0xf bank_mask:0xf
	v_add_f32_dpp v74, v74, v74 row_ror:4 row_mask:0xf bank_mask:0xf
	s_nop 1
	v_add_f32_dpp v76, v76, v76 row_ror:8 row_mask:0xf bank_mask:0xf
	v_add_f32_dpp v74, v74, v74 row_ror:8 row_mask:0xf bank_mask:0xf
	s_nop 1
	v_mov_b32_e32 v77, v76
	v_mov_b32_e32 v75, v74
	s_nop 1
	v_permlane16_swap_b32_e32 v77, v76
	v_permlane16_swap_b32_e32 v75, v74
	s_nop 1
	v_add_f32_e32 v76, v77, v76
	v_add_f32_e32 v74, v75, v74
	v_mov_b32_e32 v77, v76
	v_mov_b32_e32 v75, v74
	s_nop 1
	v_permlane32_swap_b32_e32 v77, v76
	v_permlane32_swap_b32_e32 v75, v74
	s_nop 1
	v_add_f32_e32 v76, v77, v76
	v_add_f32_e32 v74, v75, v74
	v_fmamk_f32 v63, v76, 0xba800000, v63
	v_fmamk_f32 v62, v76, 0xba800000, v62
	v_fmamk_f32 v65, v76, 0xba800000, v65
	v_fmac_f32_e32 v64, 0xba800000, v76
	v_fmamk_f32 v59, v76, 0xba800000, v59
	v_fmamk_f32 v58, v76, 0xba800000, v58
	v_fmamk_f32 v61, v76, 0xba800000, v61
	v_fmac_f32_e32 v60, 0xba800000, v76
	v_fmamk_f32 v51, v76, 0xba800000, v51
	v_fmamk_f32 v50, v76, 0xba800000, v50
	v_fmamk_f32 v53, v76, 0xba800000, v53
	v_fmac_f32_e32 v52, 0xba800000, v76
	v_fmamk_f32 v57, v76, 0xba800000, v57
	v_fmamk_f32 v56, v76, 0xba800000, v56
	v_fmamk_f32 v55, v76, 0xba800000, v55
	v_fmac_f32_e32 v54, 0xba800000, v76
	v_mov_b32_e32 v83, v74
	v_pk_mul_f32 v[74:75], v[64:65], v[64:65]
	v_pk_mul_f32 v[76:77], v[62:63], v[62:63]
	v_pk_mul_f32 v[78:79], v[60:61], v[60:61]
	v_pk_mul_f32 v[80:81], v[58:59], v[58:59]
	v_pk_mov_b32 v[86:87], v[76:77], v[74:75] op_sel:[1,0]
	v_mov_b32_e32 v77, v75
	v_pk_mov_b32 v[74:75], v[80:81], v[78:79] op_sel:[1,0]
	v_mov_b32_e32 v81, v79
	v_mul_f32_e32 v82, v51, v51
	v_mul_f32_e32 v84, v53, v53
	v_fmamk_f32 v47, v83, 0xba800000, v47
	v_fmamk_f32 v46, v83, 0xba800000, v46
	v_fmamk_f32 v49, v83, 0xba800000, v49
	v_fmac_f32_e32 v48, 0xba800000, v83
	v_fmamk_f32 v43, v83, 0xba800000, v43
	v_fmamk_f32 v42, v83, 0xba800000, v42
	v_fmamk_f32 v45, v83, 0xba800000, v45
	v_fmac_f32_e32 v44, 0xba800000, v83
	v_pk_add_f32 v[76:77], v[86:87], v[76:77]
	v_pk_add_f32 v[74:75], v[74:75], v[80:81]
	v_mul_f32_e32 v91, v54, v54
	v_mul_f32_e32 v93, v55, v55
	v_mul_f32_e32 v90, v56, v56
	v_mul_f32_e32 v92, v57, v57
	v_fmamk_f32 v39, v83, 0xba800000, v39
	v_fmamk_f32 v38, v83, 0xba800000, v38
	v_fmamk_f32 v41, v83, 0xba800000, v41
	v_fmac_f32_e32 v40, 0xba800000, v83
	v_fmamk_f32 v37, v83, 0xba800000, v37
	v_fmamk_f32 v36, v83, 0xba800000, v36
	v_fmamk_f32 v35, v83, 0xba800000, v35
	v_fmac_f32_e32 v34, 0xba800000, v83
	v_pk_fma_f32 v[78:79], v[50:51], v[50:51], v[82:83] op_sel_hi:[1,1,0]
	v_pk_fma_f32 v[82:83], v[52:53], v[52:53], v[84:85] op_sel_hi:[1,1,0]
	v_pk_mul_f32 v[84:85], v[48:49], v[48:49]
	v_pk_mul_f32 v[86:87], v[46:47], v[46:47]
	v_pk_mul_f32 v[80:81], v[44:45], v[44:45]
	v_pk_mul_f32 v[88:89], v[42:43], v[42:43]
	v_pk_add_f32 v[76:77], v[76:77], v[76:77] op_sel:[0,1] op_sel_hi:[1,0]
	v_pk_add_f32 v[74:75], v[74:75], v[74:75] op_sel:[0,1] op_sel_hi:[1,0]
	v_mov_b32_e32 v79, v90
	v_mov_b32_e32 v83, v92
	v_pk_mov_b32 v[94:95], v[86:87], v[84:85] op_sel:[1,0]
	v_mov_b32_e32 v87, v85
	v_pk_mov_b32 v[84:85], v[88:89], v[80:81] op_sel:[1,0]
	v_mov_b32_e32 v89, v81
	v_mov_b32_e32 v77, v91
	v_mov_b32_e32 v75, v93
	v_mul_f32_e32 v90, v39, v39
	v_mul_f32_e32 v92, v41, v41
	v_pk_add_f32 v[78:79], v[78:79], v[82:83]
	v_pk_add_f32 v[86:87], v[94:95], v[86:87]
	v_pk_add_f32 v[84:85], v[84:85], v[88:89]
	v_pk_add_f32 v[74:75], v[76:77], v[74:75]
	v_mul_f32_e32 v96, v34, v34
	v_mul_f32_e32 v97, v35, v35
	v_mul_f32_e32 v98, v36, v36
	v_mul_f32_e32 v99, v37, v37
	v_pk_fma_f32 v[80:81], v[38:39], v[38:39], v[90:91] op_sel_hi:[1,1,0]
	v_pk_fma_f32 v[82:83], v[40:41], v[40:41], v[92:93] op_sel_hi:[1,1,0]
	v_pk_add_f32 v[76:77], v[86:87], v[86:87] op_sel:[0,1] op_sel_hi:[1,0]
	v_pk_add_f32 v[84:85], v[84:85], v[84:85] op_sel:[0,1] op_sel_hi:[1,0]
	v_pk_add_f32 v[74:75], v[74:75], v[78:79]
	v_mov_b32_e32 v81, v98
	v_mov_b32_e32 v83, v99
	v_mov_b32_e32 v77, v96
	v_mov_b32_e32 v85, v97
	v_add_f32_e32 v78, v74, v75
	v_pk_add_f32 v[80:81], v[80:81], v[82:83]
	v_pk_add_f32 v[74:75], v[76:77], v[84:85]
	v_pk_add_f32 v[74:75], v[74:75], v[80:81]
	v_mov_b32_e32 v76, v78
	s_nop 0
	v_add_f32_e32 v74, v74, v75
	s_nop 1
	v_add_f32_dpp v76, v76, v76 quad_perm:[1,0,3,2] row_mask:0xf bank_mask:0xf
	v_add_f32_dpp v74, v74, v74 quad_perm:[1,0,3,2] row_mask:0xf bank_mask:0xf
	s_nop 1
	v_add_f32_dpp v76, v76, v76 quad_perm:[2,3,0,1] row_mask:0xf bank_mask:0xf
	v_add_f32_dpp v74, v74, v74 quad_perm:[2,3,0,1] row_mask:0xf bank_mask:0xf
	s_nop 1
	v_add_f32_dpp v76, v76, v76 row_ror:4 row_mask:0xf bank_mask:0xf
	v_add_f32_dpp v74, v74, v74 row_ror:4 row_mask:0xf bank_mask:0xf
	s_nop 1
	v_add_f32_dpp v76, v76, v76 row_ror:8 row_mask:0xf bank_mask:0xf
	v_add_f32_dpp v74, v74, v74 row_ror:8 row_mask:0xf bank_mask:0xf
	s_nop 1
	v_mov_b32_e32 v77, v76
	v_mov_b32_e32 v75, v74
	s_nop 1
	v_permlane16_swap_b32_e32 v77, v76
	v_permlane16_swap_b32_e32 v75, v74
	s_nop 1
	v_add_f32_e32 v76, v77, v76
	v_add_f32_e32 v74, v75, v74
	v_mov_b32_e32 v77, v76
	v_mov_b32_e32 v75, v74
	s_nop 1
	v_permlane32_swap_b32_e32 v77, v76
	v_permlane32_swap_b32_e32 v75, v74
	s_nop 1
	v_add_f32_e32 v76, v77, v76
	v_add_f32_e32 v74, v75, v74
	v_fmamk_f32 v76, v76, 0x3a800000, v72
	v_mul_f32_e32 v77, 0x4f800000, v76
	v_cmp_gt_f32_e32 vcc, s33, v76
	v_fmamk_f32 v74, v74, 0x3a800000, v72
	v_cndmask_b32_e32 v75, v76, v77, vcc
	v_sqrt_f32_e32 v76, v75
	v_mul_f32_e32 v77, 0x4f800000, v74
	v_cmp_gt_f32_e64 s[4:5], s33, v74
	v_add_u32_e32 v78, -1, v76
	s_nop 0
	v_cndmask_b32_e64 v74, v74, v77, s[4:5]
	v_sqrt_f32_e32 v77, v74
	v_add_u32_e32 v79, 1, v76
	v_fma_f32 v80, -v78, v76, v75
	v_fma_f32 v81, -v79, v76, v75
	v_cmp_ge_f32_e64 s[6:7], 0, v80
	v_add_u32_e32 v80, 1, v77
	s_nop 0
	v_cndmask_b32_e64 v76, v76, v78, s[6:7]
	v_add_u32_e32 v78, -1, v77
	v_cmp_lt_f32_e64 s[6:7], 0, v81
	v_fma_f32 v81, -v80, v77, v74
	s_nop 0
	v_cndmask_b32_e64 v76, v76, v79, s[6:7]
	v_fma_f32 v79, -v78, v77, v74
	v_cmp_ge_f32_e64 s[6:7], 0, v79
	v_mul_f32_e32 v82, 0x37800000, v76
	v_cndmask_b32_e32 v76, v76, v82, vcc
	v_cndmask_b32_e64 v77, v77, v78, s[6:7]
	v_cmp_lt_f32_e64 s[6:7], 0, v81
	v_cmp_class_f32_e32 vcc, v75, v73
	s_nop 0
	v_cndmask_b32_e64 v77, v77, v80, s[6:7]
	v_cndmask_b32_e32 v75, v76, v75, vcc
	v_mul_f32_e32 v76, 0x37800000, v77
	v_div_scale_f32 v78, s[6:7], v75, v75, 1.0
	v_cndmask_b32_e64 v76, v77, v76, s[4:5]
	v_cmp_class_f32_e64 s[4:5], v74, v73
	v_rcp_f32_e32 v77, v78
	v_div_scale_f32 v79, vcc, 1.0, v75, 1.0
	v_cndmask_b32_e64 v76, v76, v74, s[4:5]
	v_div_scale_f32 v80, s[4:5], v76, v76, 1.0
	v_rcp_f32_e32 v82, v80
	v_fma_f32 v74, -v78, v77, 1.0
	v_fmac_f32_e32 v77, v74, v77
	v_mul_f32_e32 v74, v79, v77
	v_fma_f32 v83, -v80, v82, 1.0
	v_div_scale_f32 v81, s[4:5], 1.0, v76, 1.0
	v_fma_f32 v84, -v78, v74, v79
	v_fmac_f32_e32 v82, v83, v82
	v_fmac_f32_e32 v74, v84, v77
	v_mul_f32_e32 v83, v81, v82
	v_fma_f32 v78, -v78, v74, v79
	v_fma_f32 v79, -v80, v83, v81
	v_div_fmas_f32 v74, v78, v77, v74
	v_fmac_f32_e32 v83, v79, v82
	v_div_fixup_f32 v74, v74, v75, 1.0
	v_fma_f32 v75, -v80, v83, v81
	s_mov_b64 vcc, s[4:5]
	v_div_fmas_f32 v75, v75, v82, v83
	v_pk_mul_f32 v[62:63], v[74:75], v[62:63] op_sel_hi:[0,1]
	v_pk_mul_f32 v[64:65], v[74:75], v[64:65] op_sel_hi:[0,1]
	v_pk_mul_f32 v[58:59], v[74:75], v[58:59] op_sel_hi:[0,1]
	v_pk_mul_f32 v[60:61], v[74:75], v[60:61] op_sel_hi:[0,1]
	v_pk_mul_f32 v[50:51], v[74:75], v[50:51] op_sel_hi:[0,1]
	v_pk_mul_f32 v[52:53], v[74:75], v[52:53] op_sel_hi:[0,1]
	v_pk_mul_f32 v[54:55], v[74:75], v[54:55] op_sel_hi:[0,1]
	v_pk_mul_f32 v[56:57], v[74:75], v[56:57] op_sel_hi:[0,1]
	v_div_fixup_f32 v74, v75, v76, 1.0
	v_pk_fma_f32 v[64:65], v[4:5], v[64:65], v[8:9]
	v_pk_fma_f32 v[62:63], v[2:3], v[62:63], v[6:7]
	v_pk_fma_f32 v[52:53], v[20:21], v[52:53], v[24:25]
	v_pk_fma_f32 v[50:51], v[18:19], v[50:51], v[22:23]
	v_pk_fma_f32 v[56:57], v[28:29], v[56:57], v[32:33]
	v_pk_fma_f32 v[54:55], v[26:27], v[54:55], v[30:31]
	v_pk_mul_f32 v[46:47], v[74:75], v[46:47] op_sel_hi:[0,1]
	v_pk_mul_f32 v[48:49], v[74:75], v[48:49] op_sel_hi:[0,1]
	v_bfe_u32 v75, v62, 16, 1
	v_bfe_u32 v77, v64, 16, 1
	v_pk_fma_f32 v[60:61], v[12:13], v[60:61], v[16:17]
	v_bfe_u32 v76, v63, 16, 1
	v_bfe_u32 v78, v65, 16, 1
	v_pk_mul_f32 v[42:43], v[74:75], v[42:43] op_sel_hi:[0,1]
	v_pk_mul_f32 v[44:45], v[74:75], v[44:45] op_sel_hi:[0,1]
	v_pk_mul_f32 v[38:39], v[74:75], v[38:39] op_sel_hi:[0,1]
	v_pk_mul_f32 v[40:41], v[74:75], v[40:41] op_sel_hi:[0,1]
	v_bfe_u32 v83, v50, 16, 1
	v_bfe_u32 v84, v51, 16, 1
	v_bfe_u32 v85, v52, 16, 1
	v_bfe_u32 v86, v53, 16, 1
	v_pk_mul_f32 v[34:35], v[74:75], v[34:35] op_sel_hi:[0,1]
	v_pk_mul_f32 v[36:37], v[74:75], v[36:37] op_sel_hi:[0,1]
	v_bfe_u32 v74, v54, 16, 1
	v_bfe_u32 v87, v55, 16, 1
	v_bfe_u32 v88, v56, 16, 1
	v_bfe_u32 v89, v57, 16, 1
	v_add3_u32 v62, v62, v75, s12
	v_add3_u32 v64, v64, v77, s12
	v_bfe_u32 v82, v61, 16, 1
	v_add3_u32 v63, v63, v76, s12
	v_add3_u32 v65, v65, v78, s12
	v_add3_u32 v50, v50, v83, s12
	v_add3_u32 v75, v51, v84, s12
	v_add3_u32 v51, v52, v85, s12
	v_add3_u32 v52, v53, v86, s12
	v_add3_u32 v53, v54, v74, s12
	v_add3_u32 v54, v55, v87, s12
	v_add3_u32 v55, v56, v88, s12
	v_add3_u32 v56, v57, v89, s12
	v_lshrrev_b32_e32 v57, 16, v62
	v_lshrrev_b32_e32 v62, 16, v64
	v_add3_u32 v61, v61, v82, s12
	v_lshrrev_b32_e32 v82, 16, v50
	v_lshrrev_b32_e32 v83, 16, v51
	v_and_or_b32 v50, v63, s38, v57
	v_and_or_b32 v51, v65, s38, v62
	global_store_dwordx2 v[70:71], v[50:51], off
	s_load_dwordx2 s[4:5], s[18:19], 0x80
	v_pk_fma_f32 v[58:59], v[10:11], v[58:59], v[14:15]
	v_pk_fma_f32 v[48:49], v[4:5], v[48:49], v[8:9]
	v_bfe_u32 v79, v58, 16, 1
	v_bfe_u32 v80, v59, 16, 1
	v_pk_fma_f32 v[46:47], v[2:3], v[46:47], v[6:7]
	v_pk_fma_f32 v[42:43], v[10:11], v[42:43], v[14:15]
	v_add3_u32 v58, v58, v79, s12
	v_bfe_u32 v81, v60, 16, 1
	v_add3_u32 v59, v59, v80, s12
	v_pk_fma_f32 v[38:39], v[18:19], v[38:39], v[22:23]
	v_pk_fma_f32 v[36:37], v[28:29], v[36:37], v[32:33]
	v_pk_fma_f32 v[34:35], v[26:27], v[34:35], v[30:31]
	v_bfe_u32 v64, v46, 16, 1
	v_bfe_u32 v76, v48, 16, 1
	v_lshrrev_b32_e32 v58, 16, v58
	v_bfe_u32 v78, v42, 16, 1
	v_add3_u32 v60, v60, v81, s12
	v_bfe_u32 v74, v47, 16, 1
	v_bfe_u32 v77, v49, 16, 1
	v_bfe_u32 v79, v43, 16, 1
	v_bfe_u32 v84, v38, 16, 1
	v_lshrrev_b32_e32 v53, 16, v53
	v_bfe_u32 v88, v34, 16, 1
	v_bfe_u32 v89, v35, 16, 1
	v_bfe_u32 v90, v36, 16, 1
	v_bfe_u32 v91, v37, 16, 1
	v_add3_u32 v57, v46, v64, s12
	v_add3_u32 v48, v48, v76, s12
	v_and_or_b32 v46, v59, s38, v58
	v_add3_u32 v58, v42, v78, s12
	s_waitcnt lgkmcnt(0)
	s_add_u32 s4, s4, s36
	v_lshrrev_b32_e32 v60, 16, v60
	v_bfe_u32 v85, v39, 16, 1
	v_lshrrev_b32_e32 v55, 16, v55
	v_add3_u32 v62, v47, v74, s12
	v_add3_u32 v49, v49, v77, s12
	v_add3_u32 v59, v43, v79, s12
	v_and_or_b32 v43, v52, s38, v83
	v_add3_u32 v52, v38, v84, s12
	v_and_or_b32 v38, v54, s38, v53
	v_add3_u32 v34, v34, v88, s12
	v_add3_u32 v53, v35, v89, s12
	v_add3_u32 v35, v36, v90, s12
	v_add3_u32 v54, v37, v91, s12
	v_lshrrev_b32_e32 v36, 16, v57
	v_lshrrev_b32_e32 v37, 16, v48
	v_lshrrev_b32_e32 v48, 16, v58
	s_addc_u32 s5, s5, s37
	v_and_or_b32 v47, v61, s38, v60
	v_add3_u32 v60, v39, v85, s12
	v_and_or_b32 v39, v56, s38, v55
	v_lshrrev_b32_e32 v50, 16, v52
	v_lshrrev_b32_e32 v52, 16, v34
	v_lshrrev_b32_e32 v55, 16, v35
	v_and_or_b32 v34, v62, s38, v36
	v_and_or_b32 v35, v49, s38, v37
	v_and_or_b32 v36, v59, s38, v48
	v_lshl_add_u64 v[48:49], s[4:5], 0, v[68:69]
	v_add_co_u32_e32 v48, vcc, s39, v48
	v_pk_fma_f32 v[44:45], v[12:13], v[44:45], v[16:17]
	s_nop 0
	v_addc_co_u32_e32 v49, vcc, 0, v49, vcc
	global_store_dwordx2 v[48:49], v[34:35], off
	s_load_dwordx2 s[4:5], s[20:21], 0x80
	v_bfe_u32 v80, v44, 16, 1
	v_bfe_u32 v81, v45, 16, 1
	v_add3_u32 v44, v44, v80, s12
	v_add3_u32 v45, v45, v81, s12
	s_waitcnt lgkmcnt(0)
	s_add_u32 s4, s4, s34
	s_addc_u32 s5, s5, s35
	v_lshl_add_u64 v[34:35], s[4:5], 0, v[68:69]
	v_add_co_u32_e32 v34, vcc, s39, v34
	v_lshrrev_b32_e32 v44, 16, v44
	s_nop 0
	v_addc_co_u32_e32 v35, vcc, 0, v35, vcc
	global_store_dwordx2 v[34:35], v[46:47], off offset:512
	s_load_dwordx2 s[4:5], s[22:23], 0x80
	v_and_or_b32 v37, v45, s38, v44
	v_and_or_b32 v42, v75, s38, v82
	v_pk_fma_f32 v[40:41], v[20:21], v[40:41], v[24:25]
	v_and_or_b32 v44, v53, s38, v52
	s_waitcnt lgkmcnt(0)
	s_add_u32 s4, s4, s36
	s_addc_u32 s5, s5, s37
	v_lshl_add_u64 v[34:35], s[4:5], 0, v[68:69]
	v_add_co_u32_e32 v34, vcc, s39, v34
	v_bfe_u32 v86, v40, 16, 1
	s_nop 0
	v_addc_co_u32_e32 v35, vcc, 0, v35, vcc
	global_store_dwordx2 v[34:35], v[36:37], off offset:512
	s_load_dwordx2 s[4:5], s[24:25], 0x80
	v_bfe_u32 v87, v41, 16, 1
	v_add3_u32 v40, v40, v86, s12
	v_add3_u32 v41, v41, v87, s12
	v_lshrrev_b32_e32 v51, 16, v40
	s_waitcnt lgkmcnt(0)
	s_add_u32 s4, s4, s34
	s_addc_u32 s5, s5, s35
	v_lshl_add_u64 v[34:35], s[4:5], 0, v[68:69]
	v_add_co_u32_e32 v34, vcc, s39, v34
	v_and_or_b32 v40, v60, s38, v50
	s_nop 0
	v_addc_co_u32_e32 v35, vcc, 0, v35, vcc
	global_store_dwordx2 v[34:35], v[42:43], off offset:1024
	s_load_dwordx2 s[4:5], s[26:27], 0x80
	v_and_or_b32 v41, v41, s38, v51
	v_and_or_b32 v45, v54, s38, v55
	s_waitcnt lgkmcnt(0)
	s_add_u32 s4, s4, s36
	s_addc_u32 s5, s5, s37
	v_lshl_add_u64 v[34:35], s[4:5], 0, v[68:69]
	v_add_co_u32_e32 v34, vcc, s39, v34
	s_nop 1
	v_addc_co_u32_e32 v35, vcc, 0, v35, vcc
	global_store_dwordx2 v[34:35], v[40:41], off offset:1024
	s_load_dwordx2 s[4:5], s[28:29], 0x80
	s_waitcnt lgkmcnt(0)
	s_add_u32 s4, s4, s34
	s_addc_u32 s5, s5, s35
	v_lshl_add_u64 v[34:35], s[4:5], 0, v[68:69]
	v_add_co_u32_e32 v34, vcc, s39, v34
	s_nop 1
	v_addc_co_u32_e32 v35, vcc, 0, v35, vcc
	global_store_dwordx2 v[34:35], v[38:39], off offset:1536
	s_load_dwordx2 s[4:5], s[30:31], 0x80
	s_waitcnt lgkmcnt(0)
	s_add_u32 s4, s4, s36
	s_addc_u32 s5, s5, s37
	v_lshl_add_u64 v[34:35], s[4:5], 0, v[68:69]
	s_addk_i32 s13, 0x1000
	s_add_i32 s14, s14, 0x400000
	v_add_co_u32_e32 v34, vcc, 0x7200000, v34
	s_cmpk_gt_u32 s13, 0x6fff
	s_nop 0
	v_addc_co_u32_e32 v35, vcc, 0, v35, vcc
	global_store_dwordx2 v[34:35], v[44:45], off offset:1536
	s_cbranch_scc0 .LBB0_81
